# combo18 + E56: same mixing in the conv pass PA2 (half of the CUs start with the X/B/C column groups, Q/K groups last)
# speedup vs baseline: 1.0115x; 1.0003x over previous
.LBB0_37:
	s_cmpk_gt_i32 s50, 0x37ff
	s_cbranch_scc1 .LBB0_81
	v_lshlrev_b32_e32 v0, 3, v16
	s_lshl_b32 s8, s10, 6
	v_readlane_b32 s9, v251, 21
	v_and_b32_e32 v77, 56, v16
	v_and_b32_e32 v76, 56, v0
	s_add_i32 s34, s9, s8
	s_movk_i32 s32, 0x7fff
	s_cmpk_lg_u32 s36, 0x100
	s_cbranch_scc1 .LBB0_40
	s_movk_i32 s32, 7
	s_bitcmp1_b32 s57, 5
	s_cbranch_scc0 .LBB0_40
	s_addk_i32 s50, 0x2000
	s_lshl_b32 s8, s72, 2
	s_add_i32 s34, s34, s8
	s_branch .LBB0_40
.LBB0_39:
	s_add_i32 s50, s50, s33
	s_add_i32 s34, s34, s72
	s_add_i32 s32, s32, -1
	s_cmp_eq_u32 s32, 0
	s_cbranch_scc1 .LBB0_81
	s_cmpk_gt_i32 s50, 0x37ff
	s_cbranch_scc0 .LBB0_40
	s_cmpk_gt_u32 s32, 0x1000
	s_cbranch_scc1 .LBB0_81
	s_addk_i32 s50, -14336
	s_mul_i32 s8, s72, 7
	s_sub_i32 s34, s34, s8
